# P8 EpiRes: 7 of the 10 up-front residual loads prefetched in the tile's first K-iteration; counted waits for the other 3
# baseline (speedup 1.0000x reference)
.LBB0_1127:
	s_xor_b64 s[16:17], s[34:35], -1
	s_and_b64 s[28:29], s[34:35], exec
	s_cselect_b32 s19, s13, s25
	s_cselect_b32 s30, s12, s24
	s_cselect_b32 s34, s15, s27
	s_cselect_b32 s35, s14, s26
	s_add_u32 s24, s24, 0x20080
	s_addc_u32 s25, s25, 0
	s_add_u32 s36, s26, 0x100
	s_addc_u32 s37, s27, 0
	s_mov_b32 s38, -2
	s_waitcnt lgkmcnt(0)
	ds_read_b128 v[128:131], v186
	ds_read_b128 v[132:135], v186 offset:1024
	ds_read_b128 v[136:139], v186 offset:2048
	ds_read_b128 v[140:143], v186 offset:3072
	s_add_u32 s26, s24, 0xfffe0080
	s_addc_u32 s27, s25, -1
	s_cmp_eq_u32 s38, 4
	s_cselect_b32 s29, s19, s27
	s_cselect_b32 s28, s30, s26
	s_cselect_b32 s27, s34, s37
	s_cselect_b32 s26, s35, s36
	v_lshl_add_u64 v[182:183], s[24:25], 0, v[164:165]
	s_add_i32 m0, s42, 0xc000
	ds_read_b128 v[144:147], v187
	ds_read_b128 v[148:151], v187 offset:1024
	ds_read_b128 v[152:155], v187 offset:2048
	ds_read_b128 v[156:159], v187 offset:3072
	ds_read_b128 v[170:173], v187 offset:4096
	ds_read_b128 v[174:177], v187 offset:5120
	ds_read_b128 v[178:181], v187 offset:6144
	ds_read_b128 v[192:195], v187 offset:7168
	global_load_lds_dwordx4 v[182:183], off
	v_lshl_add_u64 v[182:183], s[24:25], 0, v[166:167]
	s_add_i32 m0, s42, 0xe000
	s_nop 0
	global_load_lds_dwordx4 v[182:183], off
	ds_read_b128 v[196:199], v188
	ds_read_b128 v[204:207], v188 offset:1024
	ds_read_b128 v[208:211], v188 offset:2048
	ds_read_b128 v[212:215], v188 offset:3072
	s_waitcnt lgkmcnt(0)
	s_waitcnt vmcnt(8)
	s_barrier
	s_setprio 1
	v_mfma_f32_16x16x32_bf16 v[124:127], v[128:131], v[144:147], 0
	v_mfma_f32_16x16x32_bf16 v[120:123], v[136:139], v[144:147], 0
	v_mfma_f32_16x16x32_bf16 v[108:111], v[128:131], v[152:155], 0
	v_mfma_f32_16x16x32_bf16 v[104:107], v[136:139], v[152:155], 0
	v_mfma_f32_16x16x32_bf16 v[92:95], v[128:131], v[170:173], 0
	v_mfma_f32_16x16x32_bf16 v[88:91], v[136:139], v[170:173], 0
	v_mfma_f32_16x16x32_bf16 v[76:79], v[128:131], v[178:181], 0
	v_mfma_f32_16x16x32_bf16 v[72:75], v[136:139], v[178:181], 0
	v_mfma_f32_16x16x32_bf16 v[124:127], v[132:135], v[148:151], v[124:127]
	v_mfma_f32_16x16x32_bf16 v[120:123], v[140:143], v[148:151], v[120:123]
	v_mfma_f32_16x16x32_bf16 v[108:111], v[132:135], v[156:159], v[108:111]
	v_mfma_f32_16x16x32_bf16 v[104:107], v[140:143], v[156:159], v[104:107]
	v_mfma_f32_16x16x32_bf16 v[92:95], v[132:135], v[174:177], v[92:95]
	v_mfma_f32_16x16x32_bf16 v[88:91], v[140:143], v[174:177], v[88:91]
	v_mfma_f32_16x16x32_bf16 v[76:79], v[132:135], v[192:195], v[76:79]
	v_mfma_f32_16x16x32_bf16 v[72:75], v[140:143], v[192:195], v[72:75]
	v_mfma_f32_16x16x32_bf16 v[116:119], v[196:199], v[144:147], 0
	v_mfma_f32_16x16x32_bf16 v[112:115], v[208:211], v[144:147], 0
	v_mfma_f32_16x16x32_bf16 v[100:103], v[196:199], v[152:155], 0
	v_mfma_f32_16x16x32_bf16 v[96:99], v[208:211], v[152:155], 0
	v_mfma_f32_16x16x32_bf16 v[84:87], v[196:199], v[170:173], 0
	v_mfma_f32_16x16x32_bf16 v[80:83], v[208:211], v[170:173], 0
	v_mfma_f32_16x16x32_bf16 v[68:71], v[196:199], v[178:181], 0
	v_mfma_f32_16x16x32_bf16 v[64:67], v[208:211], v[178:181], 0
	v_mfma_f32_16x16x32_bf16 v[116:119], v[204:207], v[148:151], v[116:119]
	v_mfma_f32_16x16x32_bf16 v[112:115], v[212:215], v[148:151], v[112:115]
	v_mfma_f32_16x16x32_bf16 v[100:103], v[204:207], v[156:159], v[100:103]
	v_mfma_f32_16x16x32_bf16 v[96:99], v[212:215], v[156:159], v[96:99]
	v_mfma_f32_16x16x32_bf16 v[84:87], v[204:207], v[174:177], v[84:87]
	v_mfma_f32_16x16x32_bf16 v[80:83], v[212:215], v[174:177], v[80:83]
	v_mfma_f32_16x16x32_bf16 v[68:71], v[204:207], v[192:195], v[68:71]
	v_mfma_f32_16x16x32_bf16 v[64:67], v[212:215], v[192:195], v[64:67]
	s_setprio 0
	s_barrier
	v_lshl_or_b32 v203, s63, 8, v185
	v_lshlrev_b32_e32 v203, 1, v203
	v_lshl_add_u32 v247, s18, 8, v184
	v_lshl_add_u32 v203, v247, 11, v203
	s_add_u32 s74, s8, 0x8000
	s_addc_u32 s75, s9, 0
	s_add_u32 s76, s8, 0x10000
	s_addc_u32 s77, s9, 0
	s_add_u32 s78, s8, 0x18000
	s_addc_u32 s79, s9, 0
	global_load_dwordx4 v[220:223], v203, s[8:9]
	global_load_dwordx4 v[224:227], v203, s[8:9] offset:64
	global_load_dwordx4 v[228:231], v203, s[74:75]
	global_load_dwordx4 v[232:235], v203, s[74:75] offset:64
	global_load_dwordx4 v[236:239], v203, s[76:77]
	global_load_dwordx4 v[240:243], v203, s[76:77] offset:64
	global_load_dwordx4 v[252:255], v203, s[78:79]
	ds_read_b128 v[144:147], v187 offset:16384
	ds_read_b128 v[148:151], v187 offset:17408
	ds_read_b128 v[152:155], v187 offset:18432
	ds_read_b128 v[156:159], v187 offset:19456
	ds_read_b128 v[170:173], v187 offset:20480
	ds_read_b128 v[174:177], v187 offset:21504
	ds_read_b128 v[178:181], v187 offset:22528
	ds_read_b128 v[192:195], v187 offset:23552
	s_mov_b32 m0, s40
	v_lshl_add_u64 v[182:183], s[26:27], 0, v[160:161]
	global_load_lds_dwordx4 v[182:183], off
	v_lshl_add_u64 v[200:201], s[26:27], 0, v[162:163]
	s_mov_b32 m0, s41
	s_nop 0
	global_load_lds_dwordx4 v[200:201], off
	s_mov_b32 m0, s42
	v_lshl_add_u64 v[216:217], s[28:29], 0, v[160:161]
	global_load_lds_dwordx4 v[216:217], off
	v_lshl_add_u64 v[218:219], s[28:29], 0, v[162:163]
	s_mov_b32 m0, s43
	s_nop 0
	global_load_lds_dwordx4 v[218:219], off
	s_add_u32 s64, s26, 0x20000
	s_addc_u32 s65, s27, 0
	s_mov_b32 m0, s44
	v_lshl_add_u64 v[248:249], s[64:65], 0, v[160:161]
	global_load_lds_dwordx4 v[248:249], off
	v_lshl_add_u64 v[248:249], s[64:65], 0, v[162:163]
	s_mov_b32 m0, s45
	s_nop 0
	global_load_lds_dwordx4 v[248:249], off
	s_waitcnt lgkmcnt(0)
	s_waitcnt vmcnt(15)
	s_barrier
	s_setprio 1
	v_mfma_f32_16x16x32_bf16 v[60:63], v[128:131], v[144:147], 0
	v_mfma_f32_16x16x32_bf16 v[56:59], v[136:139], v[144:147], 0
	v_mfma_f32_16x16x32_bf16 v[44:47], v[128:131], v[152:155], 0
	v_mfma_f32_16x16x32_bf16 v[40:43], v[136:139], v[152:155], 0
	v_mfma_f32_16x16x32_bf16 v[28:31], v[128:131], v[170:173], 0
	v_mfma_f32_16x16x32_bf16 v[24:27], v[136:139], v[170:173], 0
	v_mfma_f32_16x16x32_bf16 v[12:15], v[128:131], v[178:181], 0
	v_mfma_f32_16x16x32_bf16 v[8:11], v[136:139], v[178:181], 0
	v_mfma_f32_16x16x32_bf16 v[60:63], v[132:135], v[148:151], v[60:63]
	v_mfma_f32_16x16x32_bf16 v[56:59], v[140:143], v[148:151], v[56:59]
	v_mfma_f32_16x16x32_bf16 v[44:47], v[132:135], v[156:159], v[44:47]
	v_mfma_f32_16x16x32_bf16 v[40:43], v[140:143], v[156:159], v[40:43]
	v_mfma_f32_16x16x32_bf16 v[28:31], v[132:135], v[174:177], v[28:31]
	v_mfma_f32_16x16x32_bf16 v[24:27], v[140:143], v[174:177], v[24:27]
	v_mfma_f32_16x16x32_bf16 v[12:15], v[132:135], v[192:195], v[12:15]
	v_mfma_f32_16x16x32_bf16 v[8:11], v[140:143], v[192:195], v[8:11]
	v_mfma_f32_16x16x32_bf16 v[52:55], v[196:199], v[144:147], 0
	v_mfma_f32_16x16x32_bf16 v[48:51], v[208:211], v[144:147], 0
	v_mfma_f32_16x16x32_bf16 v[36:39], v[196:199], v[152:155], 0
	v_mfma_f32_16x16x32_bf16 v[32:35], v[208:211], v[152:155], 0
	v_mfma_f32_16x16x32_bf16 v[20:23], v[196:199], v[170:173], 0
	v_mfma_f32_16x16x32_bf16 v[16:19], v[208:211], v[170:173], 0
	v_mfma_f32_16x16x32_bf16 v[4:7], v[196:199], v[178:181], 0
	v_mfma_f32_16x16x32_bf16 v[0:3], v[208:211], v[178:181], 0
	v_mfma_f32_16x16x32_bf16 v[52:55], v[204:207], v[148:151], v[52:55]
	v_mfma_f32_16x16x32_bf16 v[48:51], v[212:215], v[148:151], v[48:51]
	v_mfma_f32_16x16x32_bf16 v[36:39], v[204:207], v[156:159], v[36:39]
	v_mfma_f32_16x16x32_bf16 v[32:35], v[212:215], v[156:159], v[32:35]
	v_mfma_f32_16x16x32_bf16 v[20:23], v[204:207], v[174:177], v[20:23]
	v_mfma_f32_16x16x32_bf16 v[16:19], v[212:215], v[174:177], v[16:19]
	v_mfma_f32_16x16x32_bf16 v[4:7], v[204:207], v[192:195], v[4:7]
	v_mfma_f32_16x16x32_bf16 v[0:3], v[212:215], v[192:195], v[0:3]
	s_setprio 0
	s_barrier
	ds_read_b128 v[128:131], v189
	ds_read_b128 v[132:135], v189 offset:1024
	ds_read_b128 v[136:139], v189 offset:2048
	ds_read_b128 v[140:143], v189 offset:3072
	s_add_u32 s28, s28, 0x20000
	s_addc_u32 s29, s29, 0
	s_mov_b32 m0, s46
	v_lshl_add_u64 v[196:197], s[28:29], 0, v[160:161]
	ds_read_b128 v[144:147], v187 offset:32768
	ds_read_b128 v[148:151], v187 offset:33792
	ds_read_b128 v[152:155], v187 offset:34816
	ds_read_b128 v[156:159], v187 offset:35840
	ds_read_b128 v[170:173], v187 offset:36864
	ds_read_b128 v[174:177], v187 offset:37888
	ds_read_b128 v[178:181], v187 offset:38912
	ds_read_b128 v[192:195], v187 offset:39936
	global_load_lds_dwordx4 v[196:197], off
	v_lshl_add_u64 v[196:197], s[28:29], 0, v[162:163]
	s_mov_b32 m0, s47
	s_nop 0
	global_load_lds_dwordx4 v[196:197], off
	ds_read_b128 v[196:199], v190
	ds_read_b128 v[204:207], v190 offset:1024
	ds_read_b128 v[208:211], v190 offset:2048
	ds_read_b128 v[212:215], v190 offset:3072
	s_waitcnt lgkmcnt(0)
	s_waitcnt vmcnt(15)
	s_barrier
	s_setprio 1
	v_mfma_f32_16x16x32_bf16 v[124:127], v[128:131], v[144:147], v[124:127]
	v_mfma_f32_16x16x32_bf16 v[120:123], v[136:139], v[144:147], v[120:123]
	v_mfma_f32_16x16x32_bf16 v[108:111], v[128:131], v[152:155], v[108:111]
	v_mfma_f32_16x16x32_bf16 v[104:107], v[136:139], v[152:155], v[104:107]
	v_mfma_f32_16x16x32_bf16 v[92:95], v[128:131], v[170:173], v[92:95]
	v_mfma_f32_16x16x32_bf16 v[88:91], v[136:139], v[170:173], v[88:91]
	v_mfma_f32_16x16x32_bf16 v[76:79], v[128:131], v[178:181], v[76:79]
	v_mfma_f32_16x16x32_bf16 v[72:75], v[136:139], v[178:181], v[72:75]
	v_mfma_f32_16x16x32_bf16 v[124:127], v[132:135], v[148:151], v[124:127]
	v_mfma_f32_16x16x32_bf16 v[120:123], v[140:143], v[148:151], v[120:123]
	v_mfma_f32_16x16x32_bf16 v[108:111], v[132:135], v[156:159], v[108:111]
	v_mfma_f32_16x16x32_bf16 v[104:107], v[140:143], v[156:159], v[104:107]
	v_mfma_f32_16x16x32_bf16 v[92:95], v[132:135], v[174:177], v[92:95]
	v_mfma_f32_16x16x32_bf16 v[88:91], v[140:143], v[174:177], v[88:91]
	v_mfma_f32_16x16x32_bf16 v[76:79], v[132:135], v[192:195], v[76:79]
	v_mfma_f32_16x16x32_bf16 v[72:75], v[140:143], v[192:195], v[72:75]
	v_mfma_f32_16x16x32_bf16 v[116:119], v[196:199], v[144:147], v[116:119]
	v_mfma_f32_16x16x32_bf16 v[112:115], v[208:211], v[144:147], v[112:115]
	v_mfma_f32_16x16x32_bf16 v[100:103], v[196:199], v[152:155], v[100:103]
	v_mfma_f32_16x16x32_bf16 v[96:99], v[208:211], v[152:155], v[96:99]
	v_mfma_f32_16x16x32_bf16 v[84:87], v[196:199], v[170:173], v[84:87]
	v_mfma_f32_16x16x32_bf16 v[80:83], v[208:211], v[170:173], v[80:83]
	v_mfma_f32_16x16x32_bf16 v[68:71], v[196:199], v[178:181], v[68:71]
	v_mfma_f32_16x16x32_bf16 v[64:67], v[208:211], v[178:181], v[64:67]
	v_mfma_f32_16x16x32_bf16 v[116:119], v[204:207], v[148:151], v[116:119]
	v_mfma_f32_16x16x32_bf16 v[112:115], v[212:215], v[148:151], v[112:115]
	v_mfma_f32_16x16x32_bf16 v[100:103], v[204:207], v[156:159], v[100:103]
	v_mfma_f32_16x16x32_bf16 v[96:99], v[212:215], v[156:159], v[96:99]
	v_mfma_f32_16x16x32_bf16 v[84:87], v[204:207], v[174:177], v[84:87]
	v_mfma_f32_16x16x32_bf16 v[80:83], v[212:215], v[174:177], v[80:83]
	v_mfma_f32_16x16x32_bf16 v[68:71], v[204:207], v[192:195], v[68:71]
	v_mfma_f32_16x16x32_bf16 v[64:67], v[212:215], v[192:195], v[64:67]
	s_setprio 0
	s_barrier
	ds_read_b128 v[144:147], v187 offset:49152
	ds_read_b128 v[148:151], v187 offset:50176
	ds_read_b128 v[152:155], v187 offset:51200
	ds_read_b128 v[156:159], v187 offset:52224
	ds_read_b128 v[170:173], v187 offset:53248
	ds_read_b128 v[174:177], v187 offset:54272
	ds_read_b128 v[178:181], v187 offset:55296
	ds_read_b128 v[192:195], v187 offset:56320
	s_mov_b32 m0, s51
	v_lshl_add_u64 v[182:183], v[182:183], 0, s[10:11]
	global_load_lds_dwordx4 v[182:183], off
	v_lshl_add_u64 v[182:183], v[200:201], 0, s[10:11]
	s_mov_b32 m0, s52
	s_nop 0
	global_load_lds_dwordx4 v[182:183], off
	s_mov_b32 m0, s53
	v_lshl_add_u64 v[182:183], v[216:217], 0, s[10:11]
	global_load_lds_dwordx4 v[182:183], off
	v_lshl_add_u64 v[182:183], v[218:219], 0, s[10:11]
	s_mov_b32 m0, s54
	s_nop 0
	global_load_lds_dwordx4 v[182:183], off
	s_add_u32 s26, s26, 0x20080
	s_addc_u32 s27, s27, 0
	s_mov_b32 m0, s55
	v_lshl_add_u64 v[248:249], s[26:27], 0, v[160:161]
	global_load_lds_dwordx4 v[248:249], off
	v_lshl_add_u64 v[248:249], s[26:27], 0, v[162:163]
	s_mov_b32 m0, s56
	s_nop 0
	global_load_lds_dwordx4 v[248:249], off
	s_waitcnt lgkmcnt(0)
	s_waitcnt vmcnt(8)
	s_barrier
	s_setprio 1
	v_mfma_f32_16x16x32_bf16 v[60:63], v[128:131], v[144:147], v[60:63]
	v_mfma_f32_16x16x32_bf16 v[56:59], v[136:139], v[144:147], v[56:59]
	v_mfma_f32_16x16x32_bf16 v[44:47], v[128:131], v[152:155], v[44:47]
	v_mfma_f32_16x16x32_bf16 v[40:43], v[136:139], v[152:155], v[40:43]
	v_mfma_f32_16x16x32_bf16 v[28:31], v[128:131], v[170:173], v[28:31]
	v_mfma_f32_16x16x32_bf16 v[24:27], v[136:139], v[170:173], v[24:27]
	v_mfma_f32_16x16x32_bf16 v[12:15], v[128:131], v[178:181], v[12:15]
	v_mfma_f32_16x16x32_bf16 v[8:11], v[136:139], v[178:181], v[8:11]
	v_mfma_f32_16x16x32_bf16 v[60:63], v[132:135], v[148:151], v[60:63]
	v_mfma_f32_16x16x32_bf16 v[56:59], v[140:143], v[148:151], v[56:59]
	v_mfma_f32_16x16x32_bf16 v[44:47], v[132:135], v[156:159], v[44:47]
	v_mfma_f32_16x16x32_bf16 v[40:43], v[140:143], v[156:159], v[40:43]
	v_mfma_f32_16x16x32_bf16 v[28:31], v[132:135], v[174:177], v[28:31]
	v_mfma_f32_16x16x32_bf16 v[24:27], v[140:143], v[174:177], v[24:27]
	v_mfma_f32_16x16x32_bf16 v[12:15], v[132:135], v[192:195], v[12:15]
	v_mfma_f32_16x16x32_bf16 v[8:11], v[140:143], v[192:195], v[8:11]
	v_mfma_f32_16x16x32_bf16 v[52:55], v[196:199], v[144:147], v[52:55]
	v_mfma_f32_16x16x32_bf16 v[48:51], v[208:211], v[144:147], v[48:51]
	v_mfma_f32_16x16x32_bf16 v[36:39], v[196:199], v[152:155], v[36:39]
	v_mfma_f32_16x16x32_bf16 v[32:35], v[208:211], v[152:155], v[32:35]
	v_mfma_f32_16x16x32_bf16 v[20:23], v[196:199], v[170:173], v[20:23]
	v_mfma_f32_16x16x32_bf16 v[16:19], v[208:211], v[170:173], v[16:19]
	v_mfma_f32_16x16x32_bf16 v[4:7], v[196:199], v[178:181], v[4:7]
	v_mfma_f32_16x16x32_bf16 v[0:3], v[208:211], v[178:181], v[0:3]
	v_mfma_f32_16x16x32_bf16 v[52:55], v[204:207], v[148:151], v[52:55]
	v_mfma_f32_16x16x32_bf16 v[48:51], v[212:215], v[148:151], v[48:51]
	v_mfma_f32_16x16x32_bf16 v[36:39], v[204:207], v[156:159], v[36:39]
	v_mfma_f32_16x16x32_bf16 v[32:35], v[212:215], v[156:159], v[32:35]
	v_mfma_f32_16x16x32_bf16 v[20:23], v[204:207], v[174:177], v[20:23]
	v_mfma_f32_16x16x32_bf16 v[16:19], v[212:215], v[174:177], v[16:19]
	v_mfma_f32_16x16x32_bf16 v[4:7], v[204:207], v[192:195], v[4:7]
	v_mfma_f32_16x16x32_bf16 v[0:3], v[212:215], v[192:195], v[0:3]
	s_setprio 0
	s_add_i32 s38, s38, 2
	s_add_u32 s24, s24, 0x100
	s_addc_u32 s25, s25, 0
	s_add_u32 s36, s36, 0x100
	s_addc_u32 s37, s37, 0
	s_cmp_gt_u32 s38, 5
	s_barrier
.LBB0_1128:
	ds_read_b128 v[128:131], v186
	ds_read_b128 v[132:135], v186 offset:1024
	ds_read_b128 v[136:139], v186 offset:2048
	ds_read_b128 v[140:143], v186 offset:3072
	s_add_u32 s26, s24, 0xfffe0080
	s_addc_u32 s27, s25, -1
	s_cmp_eq_u32 s38, 4
	s_cselect_b32 s29, s19, s27
	s_cselect_b32 s28, s30, s26
	s_cselect_b32 s27, s34, s37
	s_cselect_b32 s26, s35, s36
	v_lshl_add_u64 v[182:183], s[24:25], 0, v[164:165]
	s_add_i32 m0, s42, 0xc000
	ds_read_b128 v[144:147], v187
	ds_read_b128 v[148:151], v187 offset:1024
	ds_read_b128 v[152:155], v187 offset:2048
	ds_read_b128 v[156:159], v187 offset:3072
	ds_read_b128 v[170:173], v187 offset:4096
	ds_read_b128 v[174:177], v187 offset:5120
	ds_read_b128 v[178:181], v187 offset:6144
	ds_read_b128 v[192:195], v187 offset:7168
	global_load_lds_dwordx4 v[182:183], off
	v_lshl_add_u64 v[182:183], s[24:25], 0, v[166:167]
	s_add_i32 m0, s42, 0xe000
	s_nop 0
	global_load_lds_dwordx4 v[182:183], off
	ds_read_b128 v[196:199], v188
	ds_read_b128 v[204:207], v188 offset:1024
	ds_read_b128 v[208:211], v188 offset:2048
	ds_read_b128 v[212:215], v188 offset:3072
	s_waitcnt lgkmcnt(0)
	s_waitcnt vmcnt(8)
	s_barrier
	s_setprio 1
	v_mfma_f32_16x16x32_bf16 v[124:127], v[128:131], v[144:147], v[124:127]
	v_mfma_f32_16x16x32_bf16 v[120:123], v[136:139], v[144:147], v[120:123]
	v_mfma_f32_16x16x32_bf16 v[108:111], v[128:131], v[152:155], v[108:111]
	v_mfma_f32_16x16x32_bf16 v[104:107], v[136:139], v[152:155], v[104:107]
	v_mfma_f32_16x16x32_bf16 v[92:95], v[128:131], v[170:173], v[92:95]
	v_mfma_f32_16x16x32_bf16 v[88:91], v[136:139], v[170:173], v[88:91]
	v_mfma_f32_16x16x32_bf16 v[76:79], v[128:131], v[178:181], v[76:79]
	v_mfma_f32_16x16x32_bf16 v[72:75], v[136:139], v[178:181], v[72:75]
	v_mfma_f32_16x16x32_bf16 v[124:127], v[132:135], v[148:151], v[124:127]
	v_mfma_f32_16x16x32_bf16 v[120:123], v[140:143], v[148:151], v[120:123]
	v_mfma_f32_16x16x32_bf16 v[108:111], v[132:135], v[156:159], v[108:111]
	v_mfma_f32_16x16x32_bf16 v[104:107], v[140:143], v[156:159], v[104:107]
	v_mfma_f32_16x16x32_bf16 v[92:95], v[132:135], v[174:177], v[92:95]
	v_mfma_f32_16x16x32_bf16 v[88:91], v[140:143], v[174:177], v[88:91]
	v_mfma_f32_16x16x32_bf16 v[76:79], v[132:135], v[192:195], v[76:79]
	v_mfma_f32_16x16x32_bf16 v[72:75], v[140:143], v[192:195], v[72:75]
	v_mfma_f32_16x16x32_bf16 v[116:119], v[196:199], v[144:147], v[116:119]
	v_mfma_f32_16x16x32_bf16 v[112:115], v[208:211], v[144:147], v[112:115]
	v_mfma_f32_16x16x32_bf16 v[100:103], v[196:199], v[152:155], v[100:103]
	v_mfma_f32_16x16x32_bf16 v[96:99], v[208:211], v[152:155], v[96:99]
	v_mfma_f32_16x16x32_bf16 v[84:87], v[196:199], v[170:173], v[84:87]
	v_mfma_f32_16x16x32_bf16 v[80:83], v[208:211], v[170:173], v[80:83]
	v_mfma_f32_16x16x32_bf16 v[68:71], v[196:199], v[178:181], v[68:71]
	v_mfma_f32_16x16x32_bf16 v[64:67], v[208:211], v[178:181], v[64:67]
	v_mfma_f32_16x16x32_bf16 v[116:119], v[204:207], v[148:151], v[116:119]
	v_mfma_f32_16x16x32_bf16 v[112:115], v[212:215], v[148:151], v[112:115]
	v_mfma_f32_16x16x32_bf16 v[100:103], v[204:207], v[156:159], v[100:103]
	v_mfma_f32_16x16x32_bf16 v[96:99], v[212:215], v[156:159], v[96:99]
	v_mfma_f32_16x16x32_bf16 v[84:87], v[204:207], v[174:177], v[84:87]
	v_mfma_f32_16x16x32_bf16 v[80:83], v[212:215], v[174:177], v[80:83]
	v_mfma_f32_16x16x32_bf16 v[68:71], v[204:207], v[192:195], v[68:71]
	v_mfma_f32_16x16x32_bf16 v[64:67], v[212:215], v[192:195], v[64:67]
	s_setprio 0
	s_barrier
	ds_read_b128 v[144:147], v187 offset:16384
	ds_read_b128 v[148:151], v187 offset:17408
	ds_read_b128 v[152:155], v187 offset:18432
	ds_read_b128 v[156:159], v187 offset:19456
	ds_read_b128 v[170:173], v187 offset:20480
	ds_read_b128 v[174:177], v187 offset:21504
	ds_read_b128 v[178:181], v187 offset:22528
	ds_read_b128 v[192:195], v187 offset:23552
	s_mov_b32 m0, s40
	v_lshl_add_u64 v[182:183], s[26:27], 0, v[160:161]
	global_load_lds_dwordx4 v[182:183], off
	v_lshl_add_u64 v[200:201], s[26:27], 0, v[162:163]
	s_mov_b32 m0, s41
	s_nop 0
	global_load_lds_dwordx4 v[200:201], off
	s_mov_b32 m0, s42
	v_lshl_add_u64 v[216:217], s[28:29], 0, v[160:161]
	global_load_lds_dwordx4 v[216:217], off
	v_lshl_add_u64 v[218:219], s[28:29], 0, v[162:163]
	s_mov_b32 m0, s43
	s_nop 0
	global_load_lds_dwordx4 v[218:219], off
	s_add_u32 s64, s26, 0x20000
	s_addc_u32 s65, s27, 0
	s_mov_b32 m0, s44
	v_lshl_add_u64 v[248:249], s[64:65], 0, v[160:161]
	global_load_lds_dwordx4 v[248:249], off
	v_lshl_add_u64 v[248:249], s[64:65], 0, v[162:163]
	s_mov_b32 m0, s45
	s_nop 0
	global_load_lds_dwordx4 v[248:249], off
	s_waitcnt lgkmcnt(0)
	s_waitcnt vmcnt(8)
	s_barrier
	s_setprio 1
	v_mfma_f32_16x16x32_bf16 v[60:63], v[128:131], v[144:147], v[60:63]
	v_mfma_f32_16x16x32_bf16 v[56:59], v[136:139], v[144:147], v[56:59]
	v_mfma_f32_16x16x32_bf16 v[44:47], v[128:131], v[152:155], v[44:47]
	v_mfma_f32_16x16x32_bf16 v[40:43], v[136:139], v[152:155], v[40:43]
	v_mfma_f32_16x16x32_bf16 v[28:31], v[128:131], v[170:173], v[28:31]
	v_mfma_f32_16x16x32_bf16 v[24:27], v[136:139], v[170:173], v[24:27]
	v_mfma_f32_16x16x32_bf16 v[12:15], v[128:131], v[178:181], v[12:15]
	v_mfma_f32_16x16x32_bf16 v[8:11], v[136:139], v[178:181], v[8:11]
	v_mfma_f32_16x16x32_bf16 v[60:63], v[132:135], v[148:151], v[60:63]
	v_mfma_f32_16x16x32_bf16 v[56:59], v[140:143], v[148:151], v[56:59]
	v_mfma_f32_16x16x32_bf16 v[44:47], v[132:135], v[156:159], v[44:47]
	v_mfma_f32_16x16x32_bf16 v[40:43], v[140:143], v[156:159], v[40:43]
	v_mfma_f32_16x16x32_bf16 v[28:31], v[132:135], v[174:177], v[28:31]
	v_mfma_f32_16x16x32_bf16 v[24:27], v[140:143], v[174:177], v[24:27]
	v_mfma_f32_16x16x32_bf16 v[12:15], v[132:135], v[192:195], v[12:15]
	v_mfma_f32_16x16x32_bf16 v[8:11], v[140:143], v[192:195], v[8:11]
	v_mfma_f32_16x16x32_bf16 v[52:55], v[196:199], v[144:147], v[52:55]
	v_mfma_f32_16x16x32_bf16 v[48:51], v[208:211], v[144:147], v[48:51]
	v_mfma_f32_16x16x32_bf16 v[36:39], v[196:199], v[152:155], v[36:39]
	v_mfma_f32_16x16x32_bf16 v[32:35], v[208:211], v[152:155], v[32:35]
	v_mfma_f32_16x16x32_bf16 v[20:23], v[196:199], v[170:173], v[20:23]
	v_mfma_f32_16x16x32_bf16 v[16:19], v[208:211], v[170:173], v[16:19]
	v_mfma_f32_16x16x32_bf16 v[4:7], v[196:199], v[178:181], v[4:7]
	v_mfma_f32_16x16x32_bf16 v[0:3], v[208:211], v[178:181], v[0:3]
	v_mfma_f32_16x16x32_bf16 v[52:55], v[204:207], v[148:151], v[52:55]
	v_mfma_f32_16x16x32_bf16 v[48:51], v[212:215], v[148:151], v[48:51]
	v_mfma_f32_16x16x32_bf16 v[36:39], v[204:207], v[156:159], v[36:39]
	v_mfma_f32_16x16x32_bf16 v[32:35], v[212:215], v[156:159], v[32:35]
	v_mfma_f32_16x16x32_bf16 v[20:23], v[204:207], v[174:177], v[20:23]
	v_mfma_f32_16x16x32_bf16 v[16:19], v[212:215], v[174:177], v[16:19]
	v_mfma_f32_16x16x32_bf16 v[4:7], v[204:207], v[192:195], v[4:7]
	v_mfma_f32_16x16x32_bf16 v[0:3], v[212:215], v[192:195], v[0:3]
	s_setprio 0
	s_barrier
	ds_read_b128 v[128:131], v189
	ds_read_b128 v[132:135], v189 offset:1024
	ds_read_b128 v[136:139], v189 offset:2048
	ds_read_b128 v[140:143], v189 offset:3072
	s_add_u32 s28, s28, 0x20000
	s_addc_u32 s29, s29, 0
	s_mov_b32 m0, s46
	v_lshl_add_u64 v[196:197], s[28:29], 0, v[160:161]
	ds_read_b128 v[144:147], v187 offset:32768
	ds_read_b128 v[148:151], v187 offset:33792
	ds_read_b128 v[152:155], v187 offset:34816
	ds_read_b128 v[156:159], v187 offset:35840
	ds_read_b128 v[170:173], v187 offset:36864
	ds_read_b128 v[174:177], v187 offset:37888
	ds_read_b128 v[178:181], v187 offset:38912
	ds_read_b128 v[192:195], v187 offset:39936
	global_load_lds_dwordx4 v[196:197], off
	v_lshl_add_u64 v[196:197], s[28:29], 0, v[162:163]
	s_mov_b32 m0, s47
	s_nop 0
	global_load_lds_dwordx4 v[196:197], off
	ds_read_b128 v[196:199], v190
	ds_read_b128 v[204:207], v190 offset:1024
	ds_read_b128 v[208:211], v190 offset:2048
	ds_read_b128 v[212:215], v190 offset:3072
	s_waitcnt lgkmcnt(0)
	s_waitcnt vmcnt(8)
	s_barrier
	s_setprio 1
	v_mfma_f32_16x16x32_bf16 v[124:127], v[128:131], v[144:147], v[124:127]
	v_mfma_f32_16x16x32_bf16 v[120:123], v[136:139], v[144:147], v[120:123]
	v_mfma_f32_16x16x32_bf16 v[108:111], v[128:131], v[152:155], v[108:111]
	v_mfma_f32_16x16x32_bf16 v[104:107], v[136:139], v[152:155], v[104:107]
	v_mfma_f32_16x16x32_bf16 v[92:95], v[128:131], v[170:173], v[92:95]
	v_mfma_f32_16x16x32_bf16 v[88:91], v[136:139], v[170:173], v[88:91]
	v_mfma_f32_16x16x32_bf16 v[76:79], v[128:131], v[178:181], v[76:79]
	v_mfma_f32_16x16x32_bf16 v[72:75], v[136:139], v[178:181], v[72:75]
	v_mfma_f32_16x16x32_bf16 v[124:127], v[132:135], v[148:151], v[124:127]
	v_mfma_f32_16x16x32_bf16 v[120:123], v[140:143], v[148:151], v[120:123]
	v_mfma_f32_16x16x32_bf16 v[108:111], v[132:135], v[156:159], v[108:111]
	v_mfma_f32_16x16x32_bf16 v[104:107], v[140:143], v[156:159], v[104:107]
	v_mfma_f32_16x16x32_bf16 v[92:95], v[132:135], v[174:177], v[92:95]
	v_mfma_f32_16x16x32_bf16 v[88:91], v[140:143], v[174:177], v[88:91]
	v_mfma_f32_16x16x32_bf16 v[76:79], v[132:135], v[192:195], v[76:79]
	v_mfma_f32_16x16x32_bf16 v[72:75], v[140:143], v[192:195], v[72:75]
	v_mfma_f32_16x16x32_bf16 v[116:119], v[196:199], v[144:147], v[116:119]
	v_mfma_f32_16x16x32_bf16 v[112:115], v[208:211], v[144:147], v[112:115]
	v_mfma_f32_16x16x32_bf16 v[100:103], v[196:199], v[152:155], v[100:103]
	v_mfma_f32_16x16x32_bf16 v[96:99], v[208:211], v[152:155], v[96:99]
	v_mfma_f32_16x16x32_bf16 v[84:87], v[196:199], v[170:173], v[84:87]
	v_mfma_f32_16x16x32_bf16 v[80:83], v[208:211], v[170:173], v[80:83]
	v_mfma_f32_16x16x32_bf16 v[68:71], v[196:199], v[178:181], v[68:71]
	v_mfma_f32_16x16x32_bf16 v[64:67], v[208:211], v[178:181], v[64:67]
	v_mfma_f32_16x16x32_bf16 v[116:119], v[204:207], v[148:151], v[116:119]
	v_mfma_f32_16x16x32_bf16 v[112:115], v[212:215], v[148:151], v[112:115]
	v_mfma_f32_16x16x32_bf16 v[100:103], v[204:207], v[156:159], v[100:103]
	v_mfma_f32_16x16x32_bf16 v[96:99], v[212:215], v[156:159], v[96:99]
	v_mfma_f32_16x16x32_bf16 v[84:87], v[204:207], v[174:177], v[84:87]
	v_mfma_f32_16x16x32_bf16 v[80:83], v[212:215], v[174:177], v[80:83]
	v_mfma_f32_16x16x32_bf16 v[68:71], v[204:207], v[192:195], v[68:71]
	v_mfma_f32_16x16x32_bf16 v[64:67], v[212:215], v[192:195], v[64:67]
	s_setprio 0
	s_barrier
	ds_read_b128 v[144:147], v187 offset:49152
	ds_read_b128 v[148:151], v187 offset:50176
	ds_read_b128 v[152:155], v187 offset:51200
	ds_read_b128 v[156:159], v187 offset:52224
	ds_read_b128 v[170:173], v187 offset:53248
	ds_read_b128 v[174:177], v187 offset:54272
	ds_read_b128 v[178:181], v187 offset:55296
	ds_read_b128 v[192:195], v187 offset:56320
	s_mov_b32 m0, s51
	v_lshl_add_u64 v[182:183], v[182:183], 0, s[10:11]
	global_load_lds_dwordx4 v[182:183], off
	v_lshl_add_u64 v[182:183], v[200:201], 0, s[10:11]
	s_mov_b32 m0, s52
	s_nop 0
	global_load_lds_dwordx4 v[182:183], off
	s_mov_b32 m0, s53
	v_lshl_add_u64 v[182:183], v[216:217], 0, s[10:11]
	global_load_lds_dwordx4 v[182:183], off
	v_lshl_add_u64 v[182:183], v[218:219], 0, s[10:11]
	s_mov_b32 m0, s54
	s_nop 0
	global_load_lds_dwordx4 v[182:183], off
	s_add_u32 s26, s26, 0x20080
	s_addc_u32 s27, s27, 0
	s_mov_b32 m0, s55
	v_lshl_add_u64 v[248:249], s[26:27], 0, v[160:161]
	global_load_lds_dwordx4 v[248:249], off
	v_lshl_add_u64 v[248:249], s[26:27], 0, v[162:163]
	s_mov_b32 m0, s56
	s_nop 0
	global_load_lds_dwordx4 v[248:249], off
	s_waitcnt lgkmcnt(0)
	s_waitcnt vmcnt(8)
	s_barrier
	s_setprio 1
	v_mfma_f32_16x16x32_bf16 v[60:63], v[128:131], v[144:147], v[60:63]
	v_mfma_f32_16x16x32_bf16 v[56:59], v[136:139], v[144:147], v[56:59]
	v_mfma_f32_16x16x32_bf16 v[44:47], v[128:131], v[152:155], v[44:47]
	v_mfma_f32_16x16x32_bf16 v[40:43], v[136:139], v[152:155], v[40:43]
	v_mfma_f32_16x16x32_bf16 v[28:31], v[128:131], v[170:173], v[28:31]
	v_mfma_f32_16x16x32_bf16 v[24:27], v[136:139], v[170:173], v[24:27]
	v_mfma_f32_16x16x32_bf16 v[12:15], v[128:131], v[178:181], v[12:15]
	v_mfma_f32_16x16x32_bf16 v[8:11], v[136:139], v[178:181], v[8:11]
	v_mfma_f32_16x16x32_bf16 v[60:63], v[132:135], v[148:151], v[60:63]
	v_mfma_f32_16x16x32_bf16 v[56:59], v[140:143], v[148:151], v[56:59]
	v_mfma_f32_16x16x32_bf16 v[44:47], v[132:135], v[156:159], v[44:47]
	v_mfma_f32_16x16x32_bf16 v[40:43], v[140:143], v[156:159], v[40:43]
	v_mfma_f32_16x16x32_bf16 v[28:31], v[132:135], v[174:177], v[28:31]
	v_mfma_f32_16x16x32_bf16 v[24:27], v[140:143], v[174:177], v[24:27]
	v_mfma_f32_16x16x32_bf16 v[12:15], v[132:135], v[192:195], v[12:15]
	v_mfma_f32_16x16x32_bf16 v[8:11], v[140:143], v[192:195], v[8:11]
	v_mfma_f32_16x16x32_bf16 v[52:55], v[196:199], v[144:147], v[52:55]
	v_mfma_f32_16x16x32_bf16 v[48:51], v[208:211], v[144:147], v[48:51]
	v_mfma_f32_16x16x32_bf16 v[36:39], v[196:199], v[152:155], v[36:39]
	v_mfma_f32_16x16x32_bf16 v[32:35], v[208:211], v[152:155], v[32:35]
	v_mfma_f32_16x16x32_bf16 v[20:23], v[196:199], v[170:173], v[20:23]
	v_mfma_f32_16x16x32_bf16 v[16:19], v[208:211], v[170:173], v[16:19]
	v_mfma_f32_16x16x32_bf16 v[4:7], v[196:199], v[178:181], v[4:7]
	v_mfma_f32_16x16x32_bf16 v[0:3], v[208:211], v[178:181], v[0:3]
	v_mfma_f32_16x16x32_bf16 v[52:55], v[204:207], v[148:151], v[52:55]
	v_mfma_f32_16x16x32_bf16 v[48:51], v[212:215], v[148:151], v[48:51]
	v_mfma_f32_16x16x32_bf16 v[36:39], v[204:207], v[156:159], v[36:39]
	v_mfma_f32_16x16x32_bf16 v[32:35], v[212:215], v[156:159], v[32:35]
	v_mfma_f32_16x16x32_bf16 v[20:23], v[204:207], v[174:177], v[20:23]
	v_mfma_f32_16x16x32_bf16 v[16:19], v[212:215], v[174:177], v[16:19]
	v_mfma_f32_16x16x32_bf16 v[4:7], v[204:207], v[192:195], v[4:7]
	v_mfma_f32_16x16x32_bf16 v[0:3], v[212:215], v[192:195], v[0:3]
	s_setprio 0
	s_add_i32 s38, s38, 2
	s_add_u32 s24, s24, 0x100
	s_addc_u32 s25, s25, 0
	s_add_u32 s36, s36, 0x100
	s_addc_u32 s37, s37, 0
	s_cmp_gt_u32 s38, 5
	s_barrier
	s_cbranch_scc0 .LBB0_1128
	v_lshl_or_b32 v128, s63, 8, v185
	v_lshl_add_u32 v170, s18, 8, v184
	v_ashrrev_i32_e32 v129, 31, v128
	v_lshlrev_b64 v[174:175], 1, v[128:129]
	v_ashrrev_i32_e32 v171, 31, v170
	v_lshl_add_u64 v[128:129], s[8:9], 0, v[174:175]
	v_lshlrev_b64 v[204:205], 11, v[170:171]
	v_lshl_add_u64 v[130:131], v[128:129], 0, v[204:205]
	v_mov_b32_e32 v194, v220
	v_mov_b32_e32 v195, v221
	v_mov_b32_e32 v196, v222
	v_mov_b32_e32 v197, v223
	v_mov_b32_e32 v198, v224
	v_mov_b32_e32 v199, v225
	v_mov_b32_e32 v200, v226
	v_mov_b32_e32 v201, v227
	v_or_b32_e32 v130, 16, v170
	v_or_b32_e32 v132, 32, v170
	v_or_b32_e32 v134, 48, v170
	v_ashrrev_i32_e32 v131, 31, v130
	v_ashrrev_i32_e32 v133, 31, v132
	v_ashrrev_i32_e32 v135, 31, v134
	v_lshlrev_b64 v[182:183], 11, v[130:131]
	v_add_u32_e32 v178, 0x80, v170
	v_lshlrev_b64 v[180:181], 11, v[132:133]
	v_lshlrev_b64 v[176:177], 11, v[134:135]
	v_lshl_add_u64 v[132:133], v[128:129], 0, v[182:183]
	v_ashrrev_i32_e32 v179, 31, v178
	v_lshl_add_u64 v[134:135], v[128:129], 0, v[180:181]
	v_lshl_add_u64 v[128:129], v[128:129], 0, v[176:177]
	v_mov_b32_e32 v156, v228
	v_mov_b32_e32 v157, v229
	v_mov_b32_e32 v158, v230
	v_mov_b32_e32 v159, v231
	v_mov_b32_e32 v152, v232
	v_mov_b32_e32 v153, v233
	v_mov_b32_e32 v154, v234
	v_mov_b32_e32 v155, v235
	v_mov_b32_e32 v148, v236
	v_mov_b32_e32 v149, v237
	v_mov_b32_e32 v150, v238
	v_mov_b32_e32 v151, v239
	v_mov_b32_e32 v144, v240
	v_mov_b32_e32 v145, v241
	v_mov_b32_e32 v146, v242
	v_mov_b32_e32 v147, v243
	v_mov_b32_e32 v140, v252
	v_mov_b32_e32 v141, v253
	v_mov_b32_e32 v142, v254
	v_mov_b32_e32 v143, v255
	global_load_dwordx4 v[136:139], v[128:129], off offset:64
	v_lshlrev_b64 v[130:131], 11, v[178:179]
	v_lshl_add_u64 v[130:131], s[8:9], 0, v[130:131]
	v_lshl_add_u64 v[172:173], v[130:131], 0, v[174:175]
	global_load_dwordx4 v[132:135], v[172:173], off
	global_load_dwordx4 v[128:131], v[172:173], off offset:64
	v_and_b32_e32 v192, 64, v191
	v_xor_b32_e32 v179, 16, v191
	v_add_u32_e32 v192, 64, v192
	v_xor_b32_e32 v193, 32, v191
	v_cmp_lt_i32_e32 vcc, v179, v192
	v_lshl_add_u64 v[204:205], s[8:9], 0, v[204:205]
	v_lshl_add_u64 v[204:205], v[204:205], 0, v[174:175]
	v_cndmask_b32_e32 v179, v191, v179, vcc
	v_cmp_lt_i32_e32 vcc, v193, v192
	v_lshlrev_b32_e32 v192, 2, v179
	s_lshl_b32 s18, s63, 2
	v_cndmask_b32_e32 v193, v191, v193, vcc
	v_lshlrev_b32_e32 v179, 2, v193
	s_or_b32 s25, s18, s50
	s_mul_hi_i32 s24, s25, 0x21000
	s_mul_i32 s25, s25, 0x21000
	v_lshlrev_b32_e32 v206, 16, v194
	v_and_b32_e32 v207, 0xffff0000, v194
	v_lshlrev_b32_e32 v194, 16, v195
	v_and_b32_e32 v195, 0xffff0000, v195
	v_lshlrev_b32_e32 v208, 16, v196
	v_and_b32_e32 v209, 0xffff0000, v196
	v_lshlrev_b32_e32 v196, 16, v197
	v_and_b32_e32 v197, 0xffff0000, v197
	v_lshlrev_b32_e32 v212, 16, v200
	v_and_b32_e32 v213, 0xffff0000, v200
	v_lshlrev_b32_e32 v200, 16, v201
	v_and_b32_e32 v201, 0xffff0000, v201
	v_pk_add_f32 v[126:127], v[126:127], v[194:195]
	v_pk_add_f32 v[124:125], v[124:125], v[206:207]
	v_pk_add_f32 v[122:123], v[122:123], v[196:197]
	v_pk_add_f32 v[120:121], v[120:121], v[208:209]
	v_lshlrev_b32_e32 v210, 16, v198
	v_and_b32_e32 v211, 0xffff0000, v198
	v_lshlrev_b32_e32 v198, 16, v199
	v_and_b32_e32 v199, 0xffff0000, v199
	v_pk_add_f32 v[194:195], v[114:115], v[200:201]
	v_pk_add_f32 v[196:197], v[112:113], v[212:213]
	v_cvt_pk_bf16_f32 v112, v124, v125
	v_cvt_pk_bf16_f32 v113, v126, v127
	v_mul_f32_e32 v114, v125, v125
	v_mul_f32_e32 v115, v127, v127
	v_mul_f32_e32 v125, v121, v121
	v_mul_f32_e32 v127, v123, v123
	v_pk_add_f32 v[118:119], v[118:119], v[198:199]
	v_pk_add_f32 v[116:117], v[116:117], v[210:211]
	v_fmac_f32_e32 v114, v124, v124
	v_fmac_f32_e32 v115, v126, v126
	v_fmac_f32_e32 v125, v120, v120
	v_fmac_f32_e32 v127, v122, v122
	v_mul_f32_e32 v193, v117, v117
	v_mul_f32_e32 v198, v119, v119
	v_add_f32_e32 v114, v114, v115
	v_add_f32_e32 v115, v125, v127
	v_mul_f32_e32 v124, v197, v197
	v_mul_f32_e32 v125, v195, v195
	v_fmac_f32_e32 v193, v116, v116
	v_fmac_f32_e32 v198, v118, v118
	v_fmac_f32_e32 v124, v196, v196
	v_fmac_f32_e32 v125, v194, v194
	v_add_f32_e32 v114, v114, v115
	v_add_f32_e32 v115, v193, v198
	v_add_f32_e32 v124, v124, v125
	v_add_f32_e32 v115, v115, v124
	v_add_f32_e32 v124, v114, v115
	ds_bpermute_b32 v125, v192, v124
	v_cvt_pk_bf16_f32 v114, v120, v121
	v_cvt_pk_bf16_f32 v115, v122, v123
	global_store_dwordx4 v[204:205], v[112:115], off
	s_waitcnt lgkmcnt(0)
	s_nop 0
	v_add_f32_e32 v112, v124, v125
	ds_bpermute_b32 v113, v179, v112
	v_cvt_pk_bf16_f32 v114, v116, v117
	v_cvt_pk_bf16_f32 v115, v118, v119
	v_cvt_pk_bf16_f32 v116, v196, v197
	v_cvt_pk_bf16_f32 v117, v194, v195
	global_store_dwordx4 v[204:205], v[114:117], off offset:64
	s_and_saveexec_b64 s[18:19], s[4:5]
	s_cbranch_execz .LBB0_1131
	s_add_u32 s26, s48, s25
	s_addc_u32 s27, s49, s24
	s_waitcnt lgkmcnt(0)
	v_add_f32_e32 v114, v112, v113
	v_lshl_add_u64 v[112:113], v[170:171], 2, s[26:27]
	global_store_dword v[112:113], v114, off

.LBB0_1135:
	s_or_b64 exec, exec, s[18:19]
	v_or_b32_e32 v80, 48, v178
	s_waitcnt lgkmcnt(0)
	v_ashrrev_i32_e32 v81, 31, v80
	v_lshlrev_b64 v[80:81], 11, v[80:81]
	v_lshl_add_u64 v[80:81], s[8:9], 0, v[80:81]
	v_lshl_add_u64 v[88:89], v[80:81], 0, v[174:175]
	global_load_dwordx4 v[84:87], v[88:89], off
	global_load_dwordx4 v[80:83], v[88:89], off offset:64
	v_lshlrev_b32_e32 v92, 16, v141
	v_and_b32_e32 v93, 0xffff0000, v141
	v_lshlrev_b32_e32 v90, 16, v140
	v_and_b32_e32 v91, 0xffff0000, v140
	v_pk_add_f32 v[78:79], v[78:79], v[92:93]
	v_lshlrev_b32_e32 v92, 16, v143
	v_and_b32_e32 v93, 0xffff0000, v143
	v_pk_add_f32 v[76:77], v[76:77], v[90:91]
	v_lshlrev_b32_e32 v90, 16, v142
	v_and_b32_e32 v91, 0xffff0000, v142
	v_pk_add_f32 v[74:75], v[74:75], v[92:93]
	s_waitcnt vmcnt(16)
	v_lshlrev_b32_e32 v92, 16, v137
	v_and_b32_e32 v93, 0xffff0000, v137
	v_pk_add_f32 v[72:73], v[72:73], v[90:91]
	v_lshlrev_b32_e32 v90, 16, v136
	v_and_b32_e32 v91, 0xffff0000, v136
	v_pk_add_f32 v[70:71], v[70:71], v[92:93]
	v_lshlrev_b32_e32 v92, 16, v139
	v_and_b32_e32 v93, 0xffff0000, v139
	v_pk_add_f32 v[68:69], v[68:69], v[90:91]
	v_lshlrev_b32_e32 v90, 16, v138
	v_and_b32_e32 v91, 0xffff0000, v138
	v_pk_add_f32 v[92:93], v[66:67], v[92:93]
	v_mul_f32_e32 v66, v77, v77
	v_mul_f32_e32 v67, v79, v79
	v_pk_add_f32 v[90:91], v[64:65], v[90:91]
	v_lshl_add_u64 v[64:65], s[8:9], 0, v[176:177]
	v_fmac_f32_e32 v66, v76, v76
	v_fmac_f32_e32 v67, v78, v78
	v_lshl_add_u64 v[94:95], v[64:65], 0, v[174:175]
	v_cvt_pk_bf16_f32 v64, v76, v77
	v_add_f32_e32 v66, v66, v67
	v_mul_f32_e32 v67, v73, v73
	v_mul_f32_e32 v76, v75, v75
	v_fmac_f32_e32 v67, v72, v72
	v_fmac_f32_e32 v76, v74, v74
	v_add_f32_e32 v67, v67, v76
	v_add_f32_e32 v66, v66, v67
	v_mul_f32_e32 v67, v69, v69
	v_mul_f32_e32 v76, v71, v71
	v_fmac_f32_e32 v67, v68, v68
	v_fmac_f32_e32 v76, v70, v70
	v_add_f32_e32 v67, v67, v76
	v_mul_f32_e32 v76, v91, v91
	v_mul_f32_e32 v77, v93, v93
	v_fmac_f32_e32 v76, v90, v90
	v_fmac_f32_e32 v77, v92, v92
	v_add_f32_e32 v76, v76, v77
	v_add_f32_e32 v67, v67, v76
	v_add_f32_e32 v76, v66, v67
	ds_bpermute_b32 v77, v192, v76
	v_cvt_pk_bf16_f32 v65, v78, v79
	v_cvt_pk_bf16_f32 v66, v72, v73
	v_cvt_pk_bf16_f32 v67, v74, v75
	global_store_dwordx4 v[94:95], v[64:67], off
	s_waitcnt lgkmcnt(0)
	s_nop 0
	v_add_f32_e32 v64, v76, v77
	ds_bpermute_b32 v65, v179, v64
	v_cvt_pk_bf16_f32 v66, v68, v69
	v_cvt_pk_bf16_f32 v67, v70, v71
	v_cvt_pk_bf16_f32 v68, v90, v91
	v_cvt_pk_bf16_f32 v69, v92, v93
	global_store_dwordx4 v[94:95], v[66:69], off offset:64
	s_and_saveexec_b64 s[18:19], s[4:5]
	s_cbranch_execz .LBB0_1137
	s_add_u32 s26, s48, s25
	s_addc_u32 s27, s49, s24
	s_waitcnt lgkmcnt(0)
	v_add_f32_e32 v66, v64, v65
	v_lshl_add_u64 v[64:65], v[170:171], 2, s[26:27]
	global_store_dword v[64:65], v66, off offset:192
.LBB0_1137:
	s_or_b64 exec, exec, s[18:19]
	s_waitcnt vmcnt(17)
	v_lshlrev_b32_e32 v66, 16, v133
	v_and_b32_e32 v67, 0xffff0000, v133
	v_pk_add_f32 v[62:63], v[62:63], v[66:67]
	v_lshlrev_b32_e32 v66, 16, v135
	v_and_b32_e32 v67, 0xffff0000, v135
	v_lshlrev_b32_e32 v64, 16, v132
	s_waitcnt lgkmcnt(0)
	v_and_b32_e32 v65, 0xffff0000, v132
	v_pk_add_f32 v[58:59], v[58:59], v[66:67]
	v_lshlrev_b32_e32 v66, 16, v129
	v_and_b32_e32 v67, 0xffff0000, v129
	v_pk_add_f32 v[60:61], v[60:61], v[64:65]
	v_lshlrev_b32_e32 v64, 16, v134
	v_and_b32_e32 v65, 0xffff0000, v134
	v_pk_add_f32 v[54:55], v[54:55], v[66:67]
	v_lshlrev_b32_e32 v66, 16, v131
	v_and_b32_e32 v67, 0xffff0000, v131
	v_pk_add_f32 v[56:57], v[56:57], v[64:65]
	v_lshlrev_b32_e32 v64, 16, v128
	v_and_b32_e32 v65, 0xffff0000, v128
	v_pk_add_f32 v[66:67], v[50:51], v[66:67]
	v_mul_f32_e32 v50, v61, v61
	v_mul_f32_e32 v51, v63, v63
	v_pk_add_f32 v[52:53], v[52:53], v[64:65]
	v_lshlrev_b32_e32 v64, 16, v130
	v_and_b32_e32 v65, 0xffff0000, v130
	v_fmac_f32_e32 v50, v60, v60
	v_fmac_f32_e32 v51, v62, v62
	v_pk_add_f32 v[64:65], v[48:49], v[64:65]
	v_cvt_pk_bf16_f32 v48, v60, v61
	v_add_f32_e32 v50, v50, v51
	v_mul_f32_e32 v51, v57, v57
	v_mul_f32_e32 v60, v59, v59
	v_fmac_f32_e32 v51, v56, v56
	v_fmac_f32_e32 v60, v58, v58
	v_add_f32_e32 v51, v51, v60
	v_add_f32_e32 v50, v50, v51
	v_mul_f32_e32 v51, v53, v53
	v_mul_f32_e32 v60, v55, v55
	v_fmac_f32_e32 v51, v52, v52
	v_fmac_f32_e32 v60, v54, v54
	v_add_f32_e32 v51, v51, v60
	v_mul_f32_e32 v60, v65, v65
	v_mul_f32_e32 v61, v67, v67
	v_fmac_f32_e32 v60, v64, v64
	v_fmac_f32_e32 v61, v66, v66
	v_add_f32_e32 v60, v60, v61
	v_add_f32_e32 v51, v51, v60
	v_add_f32_e32 v60, v50, v51
	ds_bpermute_b32 v61, v192, v60
	v_cvt_pk_bf16_f32 v49, v62, v63
	v_cvt_pk_bf16_f32 v50, v56, v57
	v_cvt_pk_bf16_f32 v51, v58, v59
	global_store_dwordx4 v[172:173], v[48:51], off
	s_waitcnt lgkmcnt(0)
	s_nop 0
	v_add_f32_e32 v48, v60, v61
	ds_bpermute_b32 v49, v179, v48
	v_cvt_pk_bf16_f32 v50, v52, v53
	v_cvt_pk_bf16_f32 v51, v54, v55
	v_cvt_pk_bf16_f32 v52, v64, v65
	v_cvt_pk_bf16_f32 v53, v66, v67
	global_store_dwordx4 v[172:173], v[50:53], off offset:64
	s_and_saveexec_b64 s[18:19], s[4:5]
	s_cbranch_execz .LBB0_1139
	s_add_u32 s26, s48, s25
	s_addc_u32 s27, s49, s24
	s_waitcnt lgkmcnt(0)
	v_add_f32_e32 v50, v48, v49
	v_lshl_add_u64 v[48:49], v[170:171], 2, s[26:27]
	global_store_dword v[48:49], v50, off offset:512
